# v43 + prompt-attention loop: L2 software prefetch of the next unit's K/Q/V^T tiles (3 dummy line touches per lane) issued before each unit's compute
# speedup vs baseline: 1.0071x; 1.0041x over previous
; __device__ __forceinline__ void attn_stage_load(const Params& p, const AttnUnit u, uint4 (&sk)[6], uint4 (&sv)[6]) {
;     const int h = u.bh & 15, b = u.bh >> 4, tid = threadIdx.x;
;     const int dsh = 2 * u.br, nsub = 4096 >> dsh, k_lo = u.i_start - 128;
;     const bfu* vt = (const bfu*)(p.ws + WS_VT) + (size_t)u.br * VT_SZ + (size_t)u.bh * 64 * 4096 + u.r * nsub;
;     const bfu* kbase = (const bfu*)(p.ws + WS_PROJ) + (size_t)(b * 4096 + u.r) * NPROJ + 1024 + h * 64;
; #pragma unroll
;     for (int i = 0; i < 6; ++i) {
;         const int e = tid + 512 * i;
;         { const int key = e >> 3, c = e & 7; int ik = k_lo + key; ik = ik < 0 ? 0 : ik; sk[i] = *(const uint4*)(kbase + ((size_t)ik << dsh) * NPROJ + c * 8); }
;         { const int d = e / 48, c = e - d * 48; int ik = k_lo + c * 8; ik = ik < 0 ? 0 : ik; sv[i] = *(const uint4*)(vt + (size_t)d * 4096 + ik); }
;     }
; }
; __device__ __forceinline__ void attn_stage_store(const uint4 (&sk)[6], const uint4 (&sv)[6], unsigned char* ldsb) {
;     bfu* Kl = (bfu*)ldsb; bfu* Vl = Kl + 384 * 72; const int tid = threadIdx.x;
; #pragma unroll
;     for (int i = 0; i < 6; ++i) {
;         const int e = tid + 512 * i;
;         { const int key = e >> 3, c = e & 7; *(uint4*)(Kl + key * 72 + c * 8) = sk[i]; }
;         { const int d = e / 48, c = e - d * 48; *(uint4*)(Vl + d * 392 + c * 8) = sv[i]; }
;     }
; }
; __device__ __forceinline__ void attn_qload(const Params& p, const AttnUnit u, bf16x8 (&qf)[4]) {
;     const int h = u.bh & 15, b = u.bh >> 4, lane = threadIdx.x & 63, wave = __builtin_amdgcn_readfirstlane(threadIdx.x >> 6), l15 = lane & 15, quad = lane >> 4, dsh = 2 * u.br;
; #pragma unroll
;     for (int tt = 0; tt < 2; ++tt) {
;         const int tq = u.r + ((u.i_start + 16 * (wave * 2 + tt) + l15) << dsh);
;         const bfu* qp = (const bfu*)(p.ws + WS_PROJ) + (size_t)(b * 4096 + tq) * NPROJ + h * 64 + quad * 8;
;         qf[2 * tt] = ld8g(qp); qf[2 * tt + 1] = ld8g(qp + 32);
;     }
; }
; __device__ __forceinline__ void phase3(const Params& p, unsigned char* lds, int bid, int G) {
;     ...
;         for (int i = 0; i < nun; ++i) {
;             AttnUnit uc; ATTN_UNIT_OF(i, uc);
;             bf16x8 qf[4]; attn_qload(p, uc, qf);
;             { uint4 sk_[6], sv_[6]; attn_stage_load(p, uc, sk_, sv_); attn_stage_store(sk_, sv_, lds); }
.LBB0_340:
	s_mul_hi_i32 s14, s0, 0x2aaaaaab
	s_lshr_b32 s15, s14, 31
	s_ashr_i32 s14, s14, 3
	s_add_i32 s16, s14, s15
	s_mul_i32 s14, s16, 48
	s_sub_i32 s0, s0, s14
	s_lshl_b32 s14, s16, 3
	s_or_b32 s17, s14, s22
	s_and_b64 s[14:15], s[12:13], exec
	s_cselect_b32 s16, s17, s16
	s_ashr_i32 s14, s0, 4
	s_and_b32 s15, s0, 15
	s_and_b32 s17, s0, 3
	s_bfe_u32 s18, s0, 0x20002
	s_cmp_eq_u32 s14, 1
	s_cselect_b32 s17, s17, s15
	s_cselect_b32 s18, s18, 0
	s_cmp_lt_u32 s0, 16
	v_readfirstlane_b32 s0, v172
	s_cselect_b32 s45, 0, s17
	s_cselect_b32 s38, s15, s18
	s_lshr_b32 s39, s0, 5
	s_lshl_b32 s0, s16, 8
	s_and_b32 s0, s0, 0xfffff000
	s_lshl_b32 s15, s39, 4
	s_lshl_b32 s41, s38, 8
	s_lshl_b32 s36, s14, 1
	s_or_b32 s37, s0, s45
	s_and_b32 s44, s15, 0x7fffffe0
	s_lshl_b32 s0, s16, 7
	s_or_b32 s48, s15, 16
	s_ashr_i32 s15, s14, 31
	s_and_b32 s0, s0, 0x780
	s_lshr_b32 s46, 0x1000, s36
	s_add_i32 s49, s41, 0xffffff80
	s_lshl_b64 s[18:19], s[14:15], 25
	s_add_u32 s47, s25, s18
	s_addc_u32 s50, s26, s19
	s_ashr_i32 s17, s16, 31
	s_lshl_b64 s[20:21], s[16:17], 19
	s_add_u32 s17, s47, s20
	s_mul_i32 s45, s45, s46
	s_addc_u32 s21, s50, s21
	s_lshl_b32 s20, s45, 1
	s_add_u32 s20, s17, s20
	s_addc_u32 s21, s21, 0
	s_mul_i32 s45, s37, 0x3000
	s_mul_hi_i32 s17, s37, 0x3000
	s_add_u32 s45, s4, s45
	s_addc_u32 s17, s5, s17
	s_add_u32 s46, s45, s0
	s_addc_u32 s47, s17, 0
	v_mov_b32_e32 v23, v2
	v_or_b32_e32 v3, s49, v76
	v_lshl_add_u64 v[0:1], s[46:47], 0, v[22:23]
	v_max_i32_e32 v4, 0, v3
	v_mov_b32_e32 v5, v2
	v_lshl_add_u64 v[0:1], v[0:1], 0, s[10:11]
	v_lshlrev_b64 v[4:5], s36, v[4:5]
	v_mad_u64_u32 v[6:7], s[46:47], v4, s31, v[0:1]
	v_mov_b32_e32 v4, v7
	v_add_u32_e32 v3, s49, v40
	v_mad_u64_u32 v[4:5], s[46:47], v5, s31, v[4:5]
	v_max_i32_e32 v3, 0, v3
	v_mov_b32_e32 v25, v2
	v_mov_b32_e32 v7, v4
	v_lshl_add_u64 v[4:5], s[20:21], 0, v[24:25]
	v_lshlrev_b32_e32 v8, 1, v3
	v_mov_b32_e32 v9, v2
	v_add_u32_e32 v3, s49, v41
	v_lshl_add_u64 v[4:5], v[4:5], 0, v[8:9]
	v_max_i32_e32 v8, 0, v3
	v_lshlrev_b64 v[8:9], s36, v[8:9]
	v_mad_u64_u32 v[10:11], s[46:47], v8, s31, v[0:1]
	v_mov_b32_e32 v8, v11
	v_add_u32_e32 v3, s49, v42
	v_mad_u64_u32 v[8:9], s[46:47], v9, s31, v[8:9]
	v_max_i32_e32 v3, 0, v3
	v_mov_b32_e32 v27, v2
	v_mov_b32_e32 v11, v8
	v_lshl_add_u64 v[8:9], s[20:21], 0, v[26:27]
	v_lshlrev_b32_e32 v12, 1, v3
	v_mov_b32_e32 v13, v2
	v_lshl_add_u64 v[8:9], v[8:9], 0, v[12:13]
	v_add_u32_e32 v12, s49, v43
	v_lshlrev_b64 v[12:13], s36, v[12:13]
	v_mad_u64_u32 v[14:15], s[46:47], v12, s31, v[0:1]
	v_mov_b32_e32 v12, v15
	v_add_u32_e32 v3, s49, v44
	v_mad_u64_u32 v[12:13], s[46:47], v13, s31, v[12:13]
	v_max_i32_e32 v3, 0, v3
	v_mov_b32_e32 v29, v2
	v_mov_b32_e32 v15, v12
	v_lshl_add_u64 v[12:13], s[20:21], 0, v[28:29]
	v_lshlrev_b32_e32 v16, 1, v3
	v_mov_b32_e32 v17, v2
	v_lshl_add_u64 v[12:13], v[12:13], 0, v[16:17]
	v_add_u32_e32 v16, s49, v45
	v_lshlrev_b64 v[16:17], s36, v[16:17]
	v_mad_u64_u32 v[18:19], s[46:47], v16, s31, v[0:1]
	v_mov_b32_e32 v16, v19
	v_add_u32_e32 v3, s49, v46
	v_mad_u64_u32 v[16:17], s[46:47], v17, s31, v[16:17]
	v_max_i32_e32 v3, 0, v3
	v_mov_b32_e32 v31, v2
	v_mov_b32_e32 v19, v16
	v_lshl_add_u64 v[16:17], s[20:21], 0, v[30:31]
	v_lshlrev_b32_e32 v38, 1, v3
	v_mov_b32_e32 v39, v2
	v_lshl_add_u64 v[16:17], v[16:17], 0, v[38:39]
	v_add_u32_e32 v38, s49, v47
	v_lshlrev_b64 v[38:39], s36, v[38:39]
	v_mad_u64_u32 v[152:153], s[46:47], v38, s31, v[0:1]
	v_mov_b32_e32 v38, v153
	v_add_u32_e32 v3, s49, v48
	v_mad_u64_u32 v[38:39], s[46:47], v39, s31, v[38:39]
	v_max_i32_e32 v3, 0, v3
	v_mov_b32_e32 v33, v2
	v_mov_b32_e32 v153, v38
	v_lshl_add_u64 v[38:39], s[20:21], 0, v[32:33]
	v_lshlrev_b32_e32 v120, 1, v3
	v_mov_b32_e32 v121, v2
	v_lshl_add_u64 v[38:39], v[38:39], 0, v[120:121]
	v_add_u32_e32 v120, s49, v49
	v_lshlrev_b64 v[120:121], s36, v[120:121]
	v_mad_u64_u32 v[0:1], s[46:47], v120, s31, v[0:1]
	v_mov_b32_e32 v120, v1
	v_add_u32_e32 v3, s49, v50
	v_mad_u64_u32 v[120:121], s[46:47], v121, s31, v[120:121]
	v_max_i32_e32 v3, 0, v3
	v_mov_b32_e32 v35, v2
	v_mov_b32_e32 v1, v120
	v_lshl_add_u64 v[120:121], s[20:21], 0, v[34:35]
	v_lshlrev_b32_e32 v122, 1, v3
	v_mov_b32_e32 v123, v2
	v_lshl_add_u64 v[164:165], v[120:121], 0, v[122:123]
	v_or_b32_e32 v23, s41, v174
	global_load_dwordx4 v[120:123], v[6:7], off
	global_load_dwordx4 v[124:127], v[4:5], off
	global_load_dwordx4 v[128:131], v[10:11], off
	global_load_dwordx4 v[132:135], v[8:9], off
	global_load_dwordx4 v[136:139], v[14:15], off
	global_load_dwordx4 v[140:143], v[12:13], off
	global_load_dwordx4 v[144:147], v[18:19], off
	global_load_dwordx4 v[148:151], v[16:17], off
	s_nop 0
	global_load_dwordx4 v[152:155], v[152:153], off
	s_nop 0
	global_load_dwordx4 v[156:159], v[38:39], off
	global_load_dwordx4 v[160:163], v[0:1], off
	s_nop 0
	global_load_dwordx4 v[164:167], v[164:165], off
	v_add_u32_e32 v0, s44, v23
	v_lshlrev_b32_e32 v0, s36, v0
	v_add_u32_e32 v3, s37, v0
	v_mov_b64_e32 v[0:1], s[8:9]
	v_mad_i64_i32 v[4:5], s[44:45], v3, s31, v[0:1]
	v_add_u32_e32 v3, s48, v23
	v_lshlrev_b32_e32 v3, s36, v3
	v_add_u32_e32 v3, s37, v3
	v_mad_i64_i32 v[0:1], s[44:45], v3, s31, v[0:1]
	v_lshl_add_u64 v[4:5], v[4:5], 0, s[0:1]
	v_mov_b32_e32 v21, v2
	v_lshl_add_u64 v[0:1], v[0:1], 0, s[0:1]
	v_lshl_add_u64 v[8:9], v[4:5], 0, v[20:21]
	v_lshl_add_u64 v[0:1], v[0:1], 0, v[20:21]
	global_load_dwordx4 v[4:7], v[8:9], off
	s_nop 0
	global_load_dwordx4 v[8:11], v[8:9], off offset:64
	s_nop 0
	global_load_dwordx4 v[12:15], v[0:1], off
	global_load_dwordx4 v[16:19], v[0:1], off offset:64
	s_and_b32 s21, s16, 15
	s_add_i32 s0, s21, 1
	v_cvt_f32_ubyte0_e32 v0, s0
	v_mul_f32_e32 v1, -0.5, v0
	v_cmp_gt_f32_e32 vcc, s33, v1
	s_and_b64 s[16:17], vcc, exec
	s_cselect_b32 s0, 0xffffffc0, 0
	v_cndmask_b32_e32 v1, 0, v117, vcc
	v_fmac_f32_e32 v1, -0.5, v0
	v_exp_f32_e32 v0, v1
	s_add_u32 s16, s27, s18
	s_addc_u32 s17, s28, s19
	s_lshl_b64 s[14:15], s[14:15], 20
	s_add_u32 s18, s29, s14
	s_addc_u32 s19, s30, s15
	s_lshl_b32 s14, 1, s36
	v_cvt_f32_u32_e32 v1, s14
	v_ldexp_f32 v0, v0, s0
	s_and_b32 s0, s39, 0x7fffffe
	s_cmp_eq_u32 s38, 0
	s_cselect_b64 s[14:15], -1, 0
	s_lshl_b32 s38, s21, 7
	s_add_u32 s16, s16, s38
	v_mul_f32_e32 v0, v0, v1
	s_addc_u32 s17, s17, 0
	v_mov_b32_e32 v37, v2
	v_mul_f32_e32 v0, 0x3fb8aa3b, v0
	v_lshl_add_u64 v[38:39], s[16:17], 0, v[36:37]
	s_lshl_b32 s16, s21, 2
	v_mul_f32_e64 v21, v65, -v0
	s_add_u32 s16, s18, s16
	s_mov_b32 s20, 0
	s_waitcnt vmcnt(15)
; #define ATTN_UNIT_OF(i, U) { const int v_ = xa ? sl + 32 * (i) : bid + G * (i), rest_ = v_ % 48; U = attn_decode(xa ? x + 8 * (v_ / 48) : v_ / 48, rest_ >> 4, rest_ & 15); }
; __device__ __forceinline__ void attn_stage_store(const uint4 (&sk)[6], const uint4 (&sv)[6], unsigned char* ldsb) {
;     bfu* Kl = (bfu*)ldsb; bfu* Vl = Kl + 384 * 72; const int tid = threadIdx.x;
; #pragma unroll
;     for (int i = 0; i < 6; ++i) {
;         const int e = tid + 512 * i;
;         { const int key = e >> 3, c = e & 7; *(uint4*)(Kl + key * 72 + c * 8) = sk[i]; }
;         { const int d = e / 48, c = e - d * 48; *(uint4*)(Vl + d * 392 + c * 8) = sv[i]; }
;     }
; }
; __device__ __forceinline__ void phase3(const Params& p, unsigned char* lds, int bid, int G) {
;     ...
;         for (int i = 0; i < nun; ++i) {
;             AttnUnit uc; ATTN_UNIT_OF(i, uc);
;             bf16x8 qf[4]; attn_qload(p, uc, qf);
;             { uint4 sk_[6], sv_[6]; attn_stage_load(p, uc, sk_, sv_); attn_stage_store(sk_, sv_, lds); }
;             __syncthreads();
;             attn_compute(p, uc, lds, qf);
;             __syncthreads();
	ds_write_b128 v51, v[120:123]
	s_waitcnt vmcnt(14)
	ds_write_b128 v52, v[124:127]
	s_waitcnt vmcnt(13)
	ds_write_b128 v53, v[128:131]
	s_waitcnt vmcnt(12)
	ds_write_b128 v54, v[132:135]
	s_waitcnt vmcnt(11)
	ds_write_b128 v55, v[136:139]
	s_waitcnt vmcnt(10)
	ds_write_b128 v56, v[140:143]
	s_waitcnt vmcnt(9)
	ds_write_b128 v57, v[144:147]
	s_waitcnt vmcnt(8)
	ds_write_b128 v58, v[148:151]
	s_waitcnt vmcnt(7)
	ds_write_b128 v59, v[152:155]
	s_waitcnt vmcnt(6)
	ds_write_b128 v60, v[156:159]
	s_waitcnt vmcnt(5)
	ds_write_b128 v61, v[160:163]
	s_waitcnt vmcnt(4)
	ds_write_b128 v62, v[164:167]
	s_addc_u32 s17, s19, 0
	v_fma_f32 v25, 0, v0, v21
	v_fma_f32 v27, v65, -v0, v0
	v_fma_f32 v29, 2.0, v0, v21
	v_fmamk_f32 v31, v0, 0x40400000, v21
	v_fmamk_f32 v33, v0, 0x41800000, v21
	v_fmamk_f32 v35, v0, 0x41880000, v21
	v_fmamk_f32 v37, v0, 0x41900000, v21
	v_fmamk_f32 v119, v0, 0x41980000, v21
	v_fmamk_f32 v120, v0, 0x42000000, v21
	v_fmamk_f32 v121, v0, 0x42040000, v21
	v_fmamk_f32 v122, v0, 0x42080000, v21
	v_fmamk_f32 v123, v0, 0x420c0000, v21
	v_fmamk_f32 v124, v0, 0x42400000, v21
	v_fmamk_f32 v125, v0, 0x42440000, v21
	v_fmamk_f32 v126, v0, 0x42480000, v21
	v_fmamk_f32 v127, v0, 0x424c0000, v21
	v_fmamk_f32 v128, v0, 0x42800000, v21
	v_fmamk_f32 v129, v0, 0x42820000, v21
	v_fmamk_f32 v130, v0, 0x42840000, v21
	v_fmamk_f32 v131, v0, 0x42860000, v21
	v_fmamk_f32 v132, v0, 0x42a00000, v21
	v_fmamk_f32 v133, v0, 0x42a20000, v21
	v_fmamk_f32 v134, v0, 0x42a40000, v21
	v_fmamk_f32 v135, v0, 0x42a60000, v21
	v_fmamk_f32 v136, v0, 0x42c00000, v21
	v_fmamk_f32 v137, v0, 0x42c20000, v21
	v_fmamk_f32 v138, v0, 0x42c40000, v21
	v_fmamk_f32 v139, v0, 0x42c60000, v21
	v_fmamk_f32 v140, v0, 0x42e00000, v21
	v_fmamk_f32 v141, v0, 0x42e20000, v21
	v_fmamk_f32 v142, v0, 0x42e40000, v21
	v_fmamk_f32 v143, v0, 0x42e60000, v21
	v_fmamk_f32 v144, v0, 0x43000000, v21
	v_fmamk_f32 v145, v0, 0x43010000, v21
	v_fmamk_f32 v146, v0, 0x43020000, v21
	v_fmac_f32_e32 v21, 0x43030000, v0
	s_mov_b64 s[18:19], -1
	s_waitcnt lgkmcnt(0)
	s_barrier
	s_waitcnt vmcnt(0)
	s_add_i32 s51, s35, 1
	s_cmp_ge_u32 s51, s3
	s_cbranch_scc1 .Lp3a_pf_done
	s_cmp_lg_u32 s12, -1
	s_cbranch_scc1 .Lp3a_pf_done
	s_lshl_b32 s52, s51, 5
	s_add_i32 s52, s52, s23
	s_mul_hi_u32 s53, s52, 0xaaaaaaab
	s_lshr_b32 s53, s53, 5
	s_mul_i32 s54, s53, 48
	s_sub_i32 s54, s52, s54
	s_lshl_b32 s55, s53, 3
	s_or_b32 s55, s55, s22
	s_lshr_b32 s56, s54, 4
	s_and_b32 s57, s54, 15
	s_and_b32 s58, s57, 3
	s_lshr_b32 s59, s57, 2
	s_cmp_eq_u32 s56, 1
	s_cselect_b32 s58, s58, s57
	s_cselect_b32 s59, s59, 0
	s_cmp_eq_u32 s56, 0
	s_cselect_b32 s58, 0, s58
	s_cselect_b32 s59, s57, s59
	s_lshl_b32 s59, s59, 8
	s_lshl_b32 s60, s56, 1
	s_sub_i32 s61, s59, 0x80
	s_lshr_b32 s62, s55, 4
	s_and_b32 s63, s55, 15
	s_lshl_b32 s66, s62, 12
	s_add_i32 s66, s66, s58
	s_lshl_b32 s67, s63, 7
	s_movk_i32 s68, 0x3000
	s_add_i32 s69, s67, 0x800
	v_min_u32_e32 v221, 0x17f, v172
	v_add_u32_e32 v222, s61, v221
	v_max_i32_e32 v222, 0, v222
	v_lshlrev_b32_e32 v222, s60, v222
	v_add_u32_e32 v222, s66, v222
	v_mul_u32_u24_e32 v222, s68, v222
	v_add_u32_e32 v222, s69, v222
	global_load_dword v224, v222, s[8:9]
	v_and_b32_e32 v223, 0xff, v172
	v_add_u32_e32 v223, s59, v223
	v_lshlrev_b32_e32 v223, s60, v223
	v_add_u32_e32 v223, s66, v223
	v_mul_u32_u24_e32 v223, s68, v223
	v_add_u32_e32 v223, s67, v223
	global_load_dword v224, v223, s[8:9]
	v_mul_u32_u24_e32 v225, 0xaaab, v221
	v_lshrrev_b32_e32 v225, 18, v225
	v_mul_u32_u24_e32 v226, 6, v225
	v_sub_u32_e32 v226, v221, v226
	v_lshlrev_b32_e32 v225, 13, v225
	v_lshl_add_u32 v225, v226, 7, v225
	s_lshl_b32 s70, s56, 25
	s_lshl_b32 s71, s55, 19
	s_add_i32 s70, s70, s71
	s_lshr_b32 s71, 0x2000, s60
	s_mul_i32 s71, s71, s58
	s_add_i32 s70, s70, s71
	s_max_i32 s71, s61, 0
	s_lshl_b32 s71, s71, 1
	s_add_i32 s70, s70, s71
	v_add_u32_e32 v225, s70, v225
	s_mov_b32 s72, s25
	s_mov_b32 s73, s26
	global_load_dword v224, v225, s[72:73]
.Lp3a_pf_done:
	s_branch .LBB0_342
